# hand-written LN2 phase: partials/residual/gate/gamma/beta loads up front, modulation loads overlapped with statistics, permlane+DPP sums
# speedup vs baseline: 1.0502x; 1.0049x over previous
.LBB0_1190:
	s_or_b64 exec, exec, s[0:1]
	v_readlane_b32 s8, v254, 16
	v_readlane_b32 s9, v254, 17
	s_mov_b64 s[6:7], 0
	s_andn2_b64 vcc, exec, s[8:9]
	s_waitcnt lgkmcnt(0)
	s_barrier
	s_lshr_b32 s0, s91, 6
	s_lshl_b32 s0, s0, 2
	v_readlane_b32 s1, v254, 6
	v_lshlrev_b32_e32 v2, 4, v230
	v_add_u32_e32 v3, 0x1000, v2
	v_lshlrev_b32_e32 v202, 5, v230
	v_add_u32_e32 v203, 0x1000, v202
	v_add_u32_e32 v204, 0x2000, v202
	v_add_u32_e32 v205, 0x3000, v202
	v_mov_b32_e32 v206, 0x3727c5ac
	v_mov_b32_e32 v207, 0x3a800000
	v_mov_b32_e32 v208, 0x3fb504f3
	v_mov_b32_e32 v209, 0x3fb504f3
	s_add_i32 s0, s0, s1
.Lln2_loop:
	s_waitcnt vmcnt(0)
	s_cmp_ge_i32 s0, s80
	s_cbranch_scc1 .Lln2_end
	v_readlane_b32 s2, v251, 0
	v_readlane_b32 s3, v251, 1
	v_readlane_b32 s64, v254, 53
	s_nop 4
	s_load_dwordx4 s[20:23], s[2:3], 0xd8
	s_load_dwordx2 s[6:7], s[2:3], 0xe8
	s_lshr_b32 s16, s0, 10
	s_sub_i32 s16, s16, 3
	s_cmp_lt_u32 s0, 0x1000
	s_cselect_b32 s16, 0, s16
	s_mul_i32 s16, s16, 0x6000
	s_mul_i32 s1, s64, 0x1e000
	s_add_i32 s1, s1, s16
	s_add_i32 s1, s1, 0x4a05000
	s_add_u32 s8, s62, s1
	s_addc_u32 s9, s63, 0
	s_add_i32 s1, s16, 0x4a1e000
	s_add_u32 s14, s62, s1
	s_addc_u32 s15, s63, 0
	s_add_u32 s16, s14, 0x1000
	s_addc_u32 s17, s15, 0
	s_lshl_b32 s1, s0, 11
	s_add_u32 s18, s62, s1
	s_addc_u32 s19, s63, 0
	s_add_u32 s2, s18, 0xc23e000
	s_addc_u32 s3, s19, 0
	s_add_u32 s4, s18, 0x5a3e000
	s_addc_u32 s5, s19, 0
	s_add_u32 s18, s18, 0x4a3e000
	s_addc_u32 s19, s19, 0
	s_lshl_b32 s1, s64, 12
	s_waitcnt lgkmcnt(0)
	s_add_u32 s10, s20, s1
	s_addc_u32 s11, s21, 0
	s_add_u32 s12, s22, s1
	s_addc_u32 s13, s23, 0
	s_lshl_b32 s1, s0, 12
	s_add_u32 s6, s6, s1
	s_addc_u32 s7, s7, 0
	global_load_dwordx4 v[100:103], v202, s[8:9]
	global_load_dwordx4 v[104:107], v202, s[8:9] offset:16
	global_load_dwordx4 v[108:111], v202, s[8:9] offset:2048
	global_load_dwordx4 v[112:115], v202, s[8:9] offset:2064
	global_load_dwordx4 v[118:121], v2, s[2:3]
	global_load_dwordx4 v[122:125], v2, s[2:3] offset:1024
	global_load_dwordx4 v[150:153], v2, s[4:5]
	global_load_dwordx4 v[154:157], v2, s[4:5] offset:1024
	global_load_dwordx4 v[4:7], v202, s[6:7]
	global_load_dwordx4 v[8:11], v202, s[6:7] offset:16
	global_load_dwordx4 v[12:15], v202, s[6:7] offset:2048
	global_load_dwordx4 v[16:19], v202, s[6:7] offset:2064
	global_load_dwordx4 v[126:129], v2, s[2:3] offset:2048
	global_load_dwordx4 v[130:133], v2, s[2:3] offset:3072
	global_load_dwordx4 v[158:161], v2, s[4:5] offset:2048
	global_load_dwordx4 v[162:165], v2, s[4:5] offset:3072
	global_load_dwordx4 v[20:23], v203, s[6:7]
	global_load_dwordx4 v[24:27], v203, s[6:7] offset:16
	global_load_dwordx4 v[28:31], v203, s[6:7] offset:2048
	global_load_dwordx4 v[32:35], v203, s[6:7] offset:2064
	global_load_dwordx4 v[134:137], v3, s[2:3]
	global_load_dwordx4 v[138:141], v3, s[2:3] offset:1024
	global_load_dwordx4 v[166:169], v3, s[4:5]
	global_load_dwordx4 v[170:173], v3, s[4:5] offset:1024
	global_load_dwordx4 v[36:39], v204, s[6:7]
	global_load_dwordx4 v[40:43], v204, s[6:7] offset:16
	global_load_dwordx4 v[44:47], v204, s[6:7] offset:2048
	global_load_dwordx4 v[48:51], v204, s[6:7] offset:2064
	global_load_dwordx4 v[142:145], v3, s[2:3] offset:2048
	global_load_dwordx4 v[146:149], v3, s[2:3] offset:3072
	global_load_dwordx4 v[174:177], v3, s[4:5] offset:2048
	global_load_dwordx4 v[178:181], v3, s[4:5] offset:3072
	global_load_dwordx4 v[52:55], v205, s[6:7]
	global_load_dwordx4 v[56:59], v205, s[6:7] offset:16
	global_load_dwordx4 v[60:63], v205, s[6:7] offset:2048
	global_load_dwordx4 v[64:67], v205, s[6:7] offset:2064
	global_load_dwordx4 v[68:71], v202, s[10:11]
	global_load_dwordx4 v[72:75], v202, s[10:11] offset:16
	global_load_dwordx4 v[76:79], v202, s[10:11] offset:2048
	global_load_dwordx4 v[80:83], v202, s[10:11] offset:2064
	global_load_dwordx4 v[84:87], v202, s[12:13]
	global_load_dwordx4 v[88:91], v202, s[12:13] offset:16
	global_load_dwordx4 v[92:95], v202, s[12:13] offset:2048
	global_load_dwordx4 v[96:99], v202, s[12:13] offset:2064
	s_waitcnt vmcnt(32)
	v_lshlrev_b32_e32 v182, 16, v118
	v_and_b32_e32 v183, 0xffff0000, v118
	v_lshlrev_b32_e32 v184, 16, v119
	v_and_b32_e32 v185, 0xffff0000, v119
	v_lshlrev_b32_e32 v186, 16, v120
	v_and_b32_e32 v187, 0xffff0000, v120
	v_lshlrev_b32_e32 v188, 16, v121
	v_and_b32_e32 v189, 0xffff0000, v121
	v_lshlrev_b32_e32 v190, 16, v150
	v_and_b32_e32 v191, 0xffff0000, v150
	v_lshlrev_b32_e32 v192, 16, v151
	v_and_b32_e32 v193, 0xffff0000, v151
	v_lshlrev_b32_e32 v194, 16, v152
	v_and_b32_e32 v195, 0xffff0000, v152
	v_lshlrev_b32_e32 v196, 16, v153
	v_and_b32_e32 v197, 0xffff0000, v153
	v_pk_add_f32 v[182:183], v[182:183], v[190:191]
	v_pk_add_f32 v[184:185], v[184:185], v[192:193]
	v_pk_add_f32 v[186:187], v[186:187], v[194:195]
	v_pk_add_f32 v[188:189], v[188:189], v[196:197]
	v_pk_mul_f32 v[4:5], v[4:5], v[208:209]
	v_pk_mul_f32 v[6:7], v[6:7], v[208:209]
	v_pk_mul_f32 v[8:9], v[8:9], v[208:209]
	v_pk_mul_f32 v[10:11], v[10:11], v[208:209]
	v_pk_fma_f32 v[4:5], v[100:101], v[182:183], v[4:5]
	v_pk_fma_f32 v[6:7], v[102:103], v[184:185], v[6:7]
	v_pk_fma_f32 v[8:9], v[104:105], v[186:187], v[8:9]
	v_pk_fma_f32 v[10:11], v[106:107], v[188:189], v[10:11]
	v_lshlrev_b32_e32 v182, 16, v122
	v_and_b32_e32 v183, 0xffff0000, v122
	v_lshlrev_b32_e32 v184, 16, v123
	v_and_b32_e32 v185, 0xffff0000, v123
	v_lshlrev_b32_e32 v186, 16, v124
	v_and_b32_e32 v187, 0xffff0000, v124
	v_lshlrev_b32_e32 v188, 16, v125
	v_and_b32_e32 v189, 0xffff0000, v125
	v_lshlrev_b32_e32 v190, 16, v154
	v_and_b32_e32 v191, 0xffff0000, v154
	v_lshlrev_b32_e32 v192, 16, v155
	v_and_b32_e32 v193, 0xffff0000, v155
	v_lshlrev_b32_e32 v194, 16, v156
	v_and_b32_e32 v195, 0xffff0000, v156
	v_lshlrev_b32_e32 v196, 16, v157
	v_and_b32_e32 v197, 0xffff0000, v157
	v_pk_add_f32 v[182:183], v[182:183], v[190:191]
	v_pk_add_f32 v[184:185], v[184:185], v[192:193]
	v_pk_add_f32 v[186:187], v[186:187], v[194:195]
	v_pk_add_f32 v[188:189], v[188:189], v[196:197]
	v_pk_mul_f32 v[12:13], v[12:13], v[208:209]
	v_pk_mul_f32 v[14:15], v[14:15], v[208:209]
	v_pk_mul_f32 v[16:17], v[16:17], v[208:209]
	v_pk_mul_f32 v[18:19], v[18:19], v[208:209]
	v_pk_fma_f32 v[12:13], v[108:109], v[182:183], v[12:13]
	v_pk_fma_f32 v[14:15], v[110:111], v[184:185], v[14:15]
	v_pk_fma_f32 v[16:17], v[112:113], v[186:187], v[16:17]
	v_pk_fma_f32 v[18:19], v[114:115], v[188:189], v[18:19]
	s_waitcnt vmcnt(24)
	v_lshlrev_b32_e32 v182, 16, v126
	v_and_b32_e32 v183, 0xffff0000, v126
	v_lshlrev_b32_e32 v184, 16, v127
	v_and_b32_e32 v185, 0xffff0000, v127
	v_lshlrev_b32_e32 v186, 16, v128
	v_and_b32_e32 v187, 0xffff0000, v128
	v_lshlrev_b32_e32 v188, 16, v129
	v_and_b32_e32 v189, 0xffff0000, v129
	v_lshlrev_b32_e32 v190, 16, v158
	v_and_b32_e32 v191, 0xffff0000, v158
	v_lshlrev_b32_e32 v192, 16, v159
	v_and_b32_e32 v193, 0xffff0000, v159
	v_lshlrev_b32_e32 v194, 16, v160
	v_and_b32_e32 v195, 0xffff0000, v160
	v_lshlrev_b32_e32 v196, 16, v161
	v_and_b32_e32 v197, 0xffff0000, v161
	v_pk_add_f32 v[182:183], v[182:183], v[190:191]
	v_pk_add_f32 v[184:185], v[184:185], v[192:193]
	v_pk_add_f32 v[186:187], v[186:187], v[194:195]
	v_pk_add_f32 v[188:189], v[188:189], v[196:197]
	v_pk_mul_f32 v[20:21], v[20:21], v[208:209]
	v_pk_mul_f32 v[22:23], v[22:23], v[208:209]
	v_pk_mul_f32 v[24:25], v[24:25], v[208:209]
	v_pk_mul_f32 v[26:27], v[26:27], v[208:209]
	v_pk_fma_f32 v[20:21], v[100:101], v[182:183], v[20:21]
	v_pk_fma_f32 v[22:23], v[102:103], v[184:185], v[22:23]
	v_pk_fma_f32 v[24:25], v[104:105], v[186:187], v[24:25]
	v_pk_fma_f32 v[26:27], v[106:107], v[188:189], v[26:27]
	v_lshlrev_b32_e32 v182, 16, v130
	v_and_b32_e32 v183, 0xffff0000, v130
	v_lshlrev_b32_e32 v184, 16, v131
	v_and_b32_e32 v185, 0xffff0000, v131
	v_lshlrev_b32_e32 v186, 16, v132
	v_and_b32_e32 v187, 0xffff0000, v132
	v_lshlrev_b32_e32 v188, 16, v133
	v_and_b32_e32 v189, 0xffff0000, v133
	v_lshlrev_b32_e32 v190, 16, v162
	v_and_b32_e32 v191, 0xffff0000, v162
	v_lshlrev_b32_e32 v192, 16, v163
	v_and_b32_e32 v193, 0xffff0000, v163
	v_lshlrev_b32_e32 v194, 16, v164
	v_and_b32_e32 v195, 0xffff0000, v164
	v_lshlrev_b32_e32 v196, 16, v165
	v_and_b32_e32 v197, 0xffff0000, v165
	v_pk_add_f32 v[182:183], v[182:183], v[190:191]
	v_pk_add_f32 v[184:185], v[184:185], v[192:193]
	v_pk_add_f32 v[186:187], v[186:187], v[194:195]
	v_pk_add_f32 v[188:189], v[188:189], v[196:197]
	v_pk_mul_f32 v[28:29], v[28:29], v[208:209]
	v_pk_mul_f32 v[30:31], v[30:31], v[208:209]
	v_pk_mul_f32 v[32:33], v[32:33], v[208:209]
	v_pk_mul_f32 v[34:35], v[34:35], v[208:209]
	v_pk_fma_f32 v[28:29], v[108:109], v[182:183], v[28:29]
	v_pk_fma_f32 v[30:31], v[110:111], v[184:185], v[30:31]
	v_pk_fma_f32 v[32:33], v[112:113], v[186:187], v[32:33]
	v_pk_fma_f32 v[34:35], v[114:115], v[188:189], v[34:35]
	s_waitcnt vmcnt(16)
	v_lshlrev_b32_e32 v182, 16, v134
	v_and_b32_e32 v183, 0xffff0000, v134
	v_lshlrev_b32_e32 v184, 16, v135
	v_and_b32_e32 v185, 0xffff0000, v135
	v_lshlrev_b32_e32 v186, 16, v136
	v_and_b32_e32 v187, 0xffff0000, v136
	v_lshlrev_b32_e32 v188, 16, v137
	v_and_b32_e32 v189, 0xffff0000, v137
	v_lshlrev_b32_e32 v190, 16, v166
	v_and_b32_e32 v191, 0xffff0000, v166
	v_lshlrev_b32_e32 v192, 16, v167
	v_and_b32_e32 v193, 0xffff0000, v167
	v_lshlrev_b32_e32 v194, 16, v168
	v_and_b32_e32 v195, 0xffff0000, v168
	v_lshlrev_b32_e32 v196, 16, v169
	v_and_b32_e32 v197, 0xffff0000, v169
	v_pk_add_f32 v[182:183], v[182:183], v[190:191]
	v_pk_add_f32 v[184:185], v[184:185], v[192:193]
	v_pk_add_f32 v[186:187], v[186:187], v[194:195]
	v_pk_add_f32 v[188:189], v[188:189], v[196:197]
	v_pk_mul_f32 v[36:37], v[36:37], v[208:209]
	v_pk_mul_f32 v[38:39], v[38:39], v[208:209]
	v_pk_mul_f32 v[40:41], v[40:41], v[208:209]
	v_pk_mul_f32 v[42:43], v[42:43], v[208:209]
	v_pk_fma_f32 v[36:37], v[100:101], v[182:183], v[36:37]
	v_pk_fma_f32 v[38:39], v[102:103], v[184:185], v[38:39]
	v_pk_fma_f32 v[40:41], v[104:105], v[186:187], v[40:41]
	v_pk_fma_f32 v[42:43], v[106:107], v[188:189], v[42:43]
	v_lshlrev_b32_e32 v182, 16, v138
	v_and_b32_e32 v183, 0xffff0000, v138
	v_lshlrev_b32_e32 v184, 16, v139
	v_and_b32_e32 v185, 0xffff0000, v139
	v_lshlrev_b32_e32 v186, 16, v140
	v_and_b32_e32 v187, 0xffff0000, v140
	v_lshlrev_b32_e32 v188, 16, v141
	v_and_b32_e32 v189, 0xffff0000, v141
	v_lshlrev_b32_e32 v190, 16, v170
	v_and_b32_e32 v191, 0xffff0000, v170
	v_lshlrev_b32_e32 v192, 16, v171
	v_and_b32_e32 v193, 0xffff0000, v171
	v_lshlrev_b32_e32 v194, 16, v172
	v_and_b32_e32 v195, 0xffff0000, v172
	v_lshlrev_b32_e32 v196, 16, v173
	v_and_b32_e32 v197, 0xffff0000, v173
	v_pk_add_f32 v[182:183], v[182:183], v[190:191]
	v_pk_add_f32 v[184:185], v[184:185], v[192:193]
	v_pk_add_f32 v[186:187], v[186:187], v[194:195]
	v_pk_add_f32 v[188:189], v[188:189], v[196:197]
	v_pk_mul_f32 v[44:45], v[44:45], v[208:209]
	v_pk_mul_f32 v[46:47], v[46:47], v[208:209]
	v_pk_mul_f32 v[48:49], v[48:49], v[208:209]
	v_pk_mul_f32 v[50:51], v[50:51], v[208:209]
	v_pk_fma_f32 v[44:45], v[108:109], v[182:183], v[44:45]
	v_pk_fma_f32 v[46:47], v[110:111], v[184:185], v[46:47]
	v_pk_fma_f32 v[48:49], v[112:113], v[186:187], v[48:49]
	v_pk_fma_f32 v[50:51], v[114:115], v[188:189], v[50:51]
	s_waitcnt vmcnt(8)
	v_lshlrev_b32_e32 v182, 16, v142
	v_and_b32_e32 v183, 0xffff0000, v142
	v_lshlrev_b32_e32 v184, 16, v143
	v_and_b32_e32 v185, 0xffff0000, v143
	v_lshlrev_b32_e32 v186, 16, v144
	v_and_b32_e32 v187, 0xffff0000, v144
	v_lshlrev_b32_e32 v188, 16, v145
	v_and_b32_e32 v189, 0xffff0000, v145
	v_lshlrev_b32_e32 v190, 16, v174
	v_and_b32_e32 v191, 0xffff0000, v174
	v_lshlrev_b32_e32 v192, 16, v175
	v_and_b32_e32 v193, 0xffff0000, v175
	v_lshlrev_b32_e32 v194, 16, v176
	v_and_b32_e32 v195, 0xffff0000, v176
	v_lshlrev_b32_e32 v196, 16, v177
	v_and_b32_e32 v197, 0xffff0000, v177
	v_pk_add_f32 v[182:183], v[182:183], v[190:191]
	v_pk_add_f32 v[184:185], v[184:185], v[192:193]
	v_pk_add_f32 v[186:187], v[186:187], v[194:195]
	v_pk_add_f32 v[188:189], v[188:189], v[196:197]
	v_pk_mul_f32 v[52:53], v[52:53], v[208:209]
	v_pk_mul_f32 v[54:55], v[54:55], v[208:209]
	v_pk_mul_f32 v[56:57], v[56:57], v[208:209]
	v_pk_mul_f32 v[58:59], v[58:59], v[208:209]
	v_pk_fma_f32 v[52:53], v[100:101], v[182:183], v[52:53]
	v_pk_fma_f32 v[54:55], v[102:103], v[184:185], v[54:55]
	v_pk_fma_f32 v[56:57], v[104:105], v[186:187], v[56:57]
	v_pk_fma_f32 v[58:59], v[106:107], v[188:189], v[58:59]
	v_lshlrev_b32_e32 v182, 16, v146
	v_and_b32_e32 v183, 0xffff0000, v146
	v_lshlrev_b32_e32 v184, 16, v147
	v_and_b32_e32 v185, 0xffff0000, v147
	v_lshlrev_b32_e32 v186, 16, v148
	v_and_b32_e32 v187, 0xffff0000, v148
	v_lshlrev_b32_e32 v188, 16, v149
	v_and_b32_e32 v189, 0xffff0000, v149
	v_lshlrev_b32_e32 v190, 16, v178
	v_and_b32_e32 v191, 0xffff0000, v178
	v_lshlrev_b32_e32 v192, 16, v179
	v_and_b32_e32 v193, 0xffff0000, v179
	v_lshlrev_b32_e32 v194, 16, v180
	v_and_b32_e32 v195, 0xffff0000, v180
	v_lshlrev_b32_e32 v196, 16, v181
	v_and_b32_e32 v197, 0xffff0000, v181
	v_pk_add_f32 v[182:183], v[182:183], v[190:191]
	v_pk_add_f32 v[184:185], v[184:185], v[192:193]
	v_pk_add_f32 v[186:187], v[186:187], v[194:195]
	v_pk_add_f32 v[188:189], v[188:189], v[196:197]
	v_pk_mul_f32 v[60:61], v[60:61], v[208:209]
	v_pk_mul_f32 v[62:63], v[62:63], v[208:209]
	v_pk_mul_f32 v[64:65], v[64:65], v[208:209]
	v_pk_mul_f32 v[66:67], v[66:67], v[208:209]
	v_pk_fma_f32 v[60:61], v[108:109], v[182:183], v[60:61]
	v_pk_fma_f32 v[62:63], v[110:111], v[184:185], v[62:63]
	v_pk_fma_f32 v[64:65], v[112:113], v[186:187], v[64:65]
	v_pk_fma_f32 v[66:67], v[114:115], v[188:189], v[66:67]
	s_cmp_lg_u32 s64, 0
	s_cbranch_scc1 .Lln2_nomod
	global_load_dwordx4 v[118:121], v202, s[16:17]
	global_load_dwordx4 v[122:125], v202, s[16:17] offset:16
	global_load_dwordx4 v[126:129], v202, s[16:17] offset:2048
	global_load_dwordx4 v[130:133], v202, s[16:17] offset:2064
	global_load_dwordx4 v[134:137], v202, s[14:15]
	global_load_dwordx4 v[138:141], v202, s[14:15] offset:16
	global_load_dwordx4 v[142:145], v202, s[14:15] offset:2048
	global_load_dwordx4 v[146:149], v202, s[14:15] offset:2064
.Lln2_nomod:
	v_pk_add_f32 v[182:183], v[4:5], v[6:7]
	v_pk_add_f32 v[182:183], v[182:183], v[8:9]
	v_pk_add_f32 v[182:183], v[182:183], v[10:11]
	v_pk_add_f32 v[182:183], v[182:183], v[12:13]
	v_pk_add_f32 v[182:183], v[182:183], v[14:15]
	v_pk_add_f32 v[182:183], v[182:183], v[16:17]
	v_pk_add_f32 v[182:183], v[182:183], v[18:19]
	v_pk_add_f32 v[184:185], v[20:21], v[22:23]
	v_pk_add_f32 v[184:185], v[184:185], v[24:25]
	v_pk_add_f32 v[184:185], v[184:185], v[26:27]
	v_pk_add_f32 v[184:185], v[184:185], v[28:29]
	v_pk_add_f32 v[184:185], v[184:185], v[30:31]
	v_pk_add_f32 v[184:185], v[184:185], v[32:33]
	v_pk_add_f32 v[184:185], v[184:185], v[34:35]
	v_pk_add_f32 v[186:187], v[36:37], v[38:39]
	v_pk_add_f32 v[186:187], v[186:187], v[40:41]
	v_pk_add_f32 v[186:187], v[186:187], v[42:43]
	v_pk_add_f32 v[186:187], v[186:187], v[44:45]
	v_pk_add_f32 v[186:187], v[186:187], v[46:47]
	v_pk_add_f32 v[186:187], v[186:187], v[48:49]
	v_pk_add_f32 v[186:187], v[186:187], v[50:51]
	v_pk_add_f32 v[188:189], v[52:53], v[54:55]
	v_pk_add_f32 v[188:189], v[188:189], v[56:57]
	v_pk_add_f32 v[188:189], v[188:189], v[58:59]
	v_pk_add_f32 v[188:189], v[188:189], v[60:61]
	v_pk_add_f32 v[188:189], v[188:189], v[62:63]
	v_pk_add_f32 v[188:189], v[188:189], v[64:65]
	v_pk_add_f32 v[188:189], v[188:189], v[66:67]
	v_add_f32_e32 v182, v182, v183
	v_add_f32_e32 v184, v184, v185
	v_add_f32_e32 v186, v186, v187
	v_add_f32_e32 v188, v188, v189
	v_mov_b32_e32 v183, v182
	v_mov_b32_e32 v185, v184
	v_mov_b32_e32 v187, v186
	v_mov_b32_e32 v189, v188
	v_permlane32_swap_b32_e32 v182, v183
	v_permlane32_swap_b32_e32 v184, v185
	v_permlane32_swap_b32_e32 v186, v187
	v_permlane32_swap_b32_e32 v188, v189
	v_add_f32_e32 v182, v182, v183
	v_add_f32_e32 v184, v184, v185
	v_add_f32_e32 v186, v186, v187
	v_add_f32_e32 v188, v188, v189
	v_mov_b32_e32 v183, v182
	v_mov_b32_e32 v185, v184
	v_mov_b32_e32 v187, v186
	v_mov_b32_e32 v189, v188
	v_permlane16_swap_b32_e32 v182, v183
	v_permlane16_swap_b32_e32 v184, v185
	v_permlane16_swap_b32_e32 v186, v187
	v_permlane16_swap_b32_e32 v188, v189
	v_add_f32_e32 v182, v182, v183
	v_add_f32_e32 v184, v184, v185
	v_add_f32_e32 v186, v186, v187
	v_add_f32_e32 v188, v188, v189
	v_add_f32_dpp v182, v182, v182 row_ror:8 row_mask:0xf bank_mask:0xf
	v_add_f32_dpp v184, v184, v184 row_ror:8 row_mask:0xf bank_mask:0xf
	v_add_f32_dpp v186, v186, v186 row_ror:8 row_mask:0xf bank_mask:0xf
	v_add_f32_dpp v188, v188, v188 row_ror:8 row_mask:0xf bank_mask:0xf
	v_add_f32_dpp v182, v182, v182 row_ror:4 row_mask:0xf bank_mask:0xf
	v_add_f32_dpp v184, v184, v184 row_ror:4 row_mask:0xf bank_mask:0xf
	v_add_f32_dpp v186, v186, v186 row_ror:4 row_mask:0xf bank_mask:0xf
	v_add_f32_dpp v188, v188, v188 row_ror:4 row_mask:0xf bank_mask:0xf
	v_add_f32_dpp v182, v182, v182 row_ror:2 row_mask:0xf bank_mask:0xf
	v_add_f32_dpp v184, v184, v184 row_ror:2 row_mask:0xf bank_mask:0xf
	v_add_f32_dpp v186, v186, v186 row_ror:2 row_mask:0xf bank_mask:0xf
	v_add_f32_dpp v188, v188, v188 row_ror:2 row_mask:0xf bank_mask:0xf
	v_add_f32_dpp v182, v182, v182 row_ror:1 row_mask:0xf bank_mask:0xf
	v_add_f32_dpp v184, v184, v184 row_ror:1 row_mask:0xf bank_mask:0xf
	v_add_f32_dpp v186, v186, v186 row_ror:1 row_mask:0xf bank_mask:0xf
	v_add_f32_dpp v188, v188, v188 row_ror:1 row_mask:0xf bank_mask:0xf
	v_mul_f32_e32 v182, v207, v182
	v_mul_f32_e32 v184, v207, v184
	v_mul_f32_e32 v186, v207, v186
	v_mul_f32_e32 v188, v207, v188
	v_pk_add_f32 v[4:5], v[4:5], v[182:183] op_sel_hi:[1,0] neg_lo:[0,1] neg_hi:[0,1]
	v_pk_add_f32 v[6:7], v[6:7], v[182:183] op_sel_hi:[1,0] neg_lo:[0,1] neg_hi:[0,1]
	v_pk_add_f32 v[8:9], v[8:9], v[182:183] op_sel_hi:[1,0] neg_lo:[0,1] neg_hi:[0,1]
	v_pk_add_f32 v[10:11], v[10:11], v[182:183] op_sel_hi:[1,0] neg_lo:[0,1] neg_hi:[0,1]
	v_pk_add_f32 v[12:13], v[12:13], v[182:183] op_sel_hi:[1,0] neg_lo:[0,1] neg_hi:[0,1]
	v_pk_add_f32 v[14:15], v[14:15], v[182:183] op_sel_hi:[1,0] neg_lo:[0,1] neg_hi:[0,1]
	v_pk_add_f32 v[16:17], v[16:17], v[182:183] op_sel_hi:[1,0] neg_lo:[0,1] neg_hi:[0,1]
	v_pk_add_f32 v[18:19], v[18:19], v[182:183] op_sel_hi:[1,0] neg_lo:[0,1] neg_hi:[0,1]
	v_pk_add_f32 v[20:21], v[20:21], v[184:185] op_sel_hi:[1,0] neg_lo:[0,1] neg_hi:[0,1]
	v_pk_add_f32 v[22:23], v[22:23], v[184:185] op_sel_hi:[1,0] neg_lo:[0,1] neg_hi:[0,1]
	v_pk_add_f32 v[24:25], v[24:25], v[184:185] op_sel_hi:[1,0] neg_lo:[0,1] neg_hi:[0,1]
	v_pk_add_f32 v[26:27], v[26:27], v[184:185] op_sel_hi:[1,0] neg_lo:[0,1] neg_hi:[0,1]
	v_pk_add_f32 v[28:29], v[28:29], v[184:185] op_sel_hi:[1,0] neg_lo:[0,1] neg_hi:[0,1]
	v_pk_add_f32 v[30:31], v[30:31], v[184:185] op_sel_hi:[1,0] neg_lo:[0,1] neg_hi:[0,1]
	v_pk_add_f32 v[32:33], v[32:33], v[184:185] op_sel_hi:[1,0] neg_lo:[0,1] neg_hi:[0,1]
	v_pk_add_f32 v[34:35], v[34:35], v[184:185] op_sel_hi:[1,0] neg_lo:[0,1] neg_hi:[0,1]
	v_pk_add_f32 v[36:37], v[36:37], v[186:187] op_sel_hi:[1,0] neg_lo:[0,1] neg_hi:[0,1]
	v_pk_add_f32 v[38:39], v[38:39], v[186:187] op_sel_hi:[1,0] neg_lo:[0,1] neg_hi:[0,1]
	v_pk_add_f32 v[40:41], v[40:41], v[186:187] op_sel_hi:[1,0] neg_lo:[0,1] neg_hi:[0,1]
	v_pk_add_f32 v[42:43], v[42:43], v[186:187] op_sel_hi:[1,0] neg_lo:[0,1] neg_hi:[0,1]
	v_pk_add_f32 v[44:45], v[44:45], v[186:187] op_sel_hi:[1,0] neg_lo:[0,1] neg_hi:[0,1]
	v_pk_add_f32 v[46:47], v[46:47], v[186:187] op_sel_hi:[1,0] neg_lo:[0,1] neg_hi:[0,1]
	v_pk_add_f32 v[48:49], v[48:49], v[186:187] op_sel_hi:[1,0] neg_lo:[0,1] neg_hi:[0,1]
	v_pk_add_f32 v[50:51], v[50:51], v[186:187] op_sel_hi:[1,0] neg_lo:[0,1] neg_hi:[0,1]
	v_pk_add_f32 v[52:53], v[52:53], v[188:189] op_sel_hi:[1,0] neg_lo:[0,1] neg_hi:[0,1]
	v_pk_add_f32 v[54:55], v[54:55], v[188:189] op_sel_hi:[1,0] neg_lo:[0,1] neg_hi:[0,1]
	v_pk_add_f32 v[56:57], v[56:57], v[188:189] op_sel_hi:[1,0] neg_lo:[0,1] neg_hi:[0,1]
	v_pk_add_f32 v[58:59], v[58:59], v[188:189] op_sel_hi:[1,0] neg_lo:[0,1] neg_hi:[0,1]
	v_pk_add_f32 v[60:61], v[60:61], v[188:189] op_sel_hi:[1,0] neg_lo:[0,1] neg_hi:[0,1]
	v_pk_add_f32 v[62:63], v[62:63], v[188:189] op_sel_hi:[1,0] neg_lo:[0,1] neg_hi:[0,1]
	v_pk_add_f32 v[64:65], v[64:65], v[188:189] op_sel_hi:[1,0] neg_lo:[0,1] neg_hi:[0,1]
	v_pk_add_f32 v[66:67], v[66:67], v[188:189] op_sel_hi:[1,0] neg_lo:[0,1] neg_hi:[0,1]
	v_pk_mul_f32 v[190:191], v[4:5], v[4:5]
	v_pk_fma_f32 v[190:191], v[6:7], v[6:7], v[190:191]
	v_pk_fma_f32 v[190:191], v[8:9], v[8:9], v[190:191]
	v_pk_fma_f32 v[190:191], v[10:11], v[10:11], v[190:191]
	v_pk_fma_f32 v[190:191], v[12:13], v[12:13], v[190:191]
	v_pk_fma_f32 v[190:191], v[14:15], v[14:15], v[190:191]
	v_pk_fma_f32 v[190:191], v[16:17], v[16:17], v[190:191]
	v_pk_fma_f32 v[190:191], v[18:19], v[18:19], v[190:191]
	v_pk_mul_f32 v[192:193], v[20:21], v[20:21]
	v_pk_fma_f32 v[192:193], v[22:23], v[22:23], v[192:193]
	v_pk_fma_f32 v[192:193], v[24:25], v[24:25], v[192:193]
	v_pk_fma_f32 v[192:193], v[26:27], v[26:27], v[192:193]
	v_pk_fma_f32 v[192:193], v[28:29], v[28:29], v[192:193]
	v_pk_fma_f32 v[192:193], v[30:31], v[30:31], v[192:193]
	v_pk_fma_f32 v[192:193], v[32:33], v[32:33], v[192:193]
	v_pk_fma_f32 v[192:193], v[34:35], v[34:35], v[192:193]
	v_pk_mul_f32 v[194:195], v[36:37], v[36:37]
	v_pk_fma_f32 v[194:195], v[38:39], v[38:39], v[194:195]
	v_pk_fma_f32 v[194:195], v[40:41], v[40:41], v[194:195]
	v_pk_fma_f32 v[194:195], v[42:43], v[42:43], v[194:195]
	v_pk_fma_f32 v[194:195], v[44:45], v[44:45], v[194:195]
	v_pk_fma_f32 v[194:195], v[46:47], v[46:47], v[194:195]
	v_pk_fma_f32 v[194:195], v[48:49], v[48:49], v[194:195]
	v_pk_fma_f32 v[194:195], v[50:51], v[50:51], v[194:195]
	v_pk_mul_f32 v[196:197], v[52:53], v[52:53]
	v_pk_fma_f32 v[196:197], v[54:55], v[54:55], v[196:197]
	v_pk_fma_f32 v[196:197], v[56:57], v[56:57], v[196:197]
	v_pk_fma_f32 v[196:197], v[58:59], v[58:59], v[196:197]
	v_pk_fma_f32 v[196:197], v[60:61], v[60:61], v[196:197]
	v_pk_fma_f32 v[196:197], v[62:63], v[62:63], v[196:197]
	v_pk_fma_f32 v[196:197], v[64:65], v[64:65], v[196:197]
	v_pk_fma_f32 v[196:197], v[66:67], v[66:67], v[196:197]
	v_add_f32_e32 v190, v190, v191
	v_add_f32_e32 v192, v192, v193
	v_add_f32_e32 v194, v194, v195
	v_add_f32_e32 v196, v196, v197
	v_mov_b32_e32 v191, v190
	v_mov_b32_e32 v193, v192
	v_mov_b32_e32 v195, v194
	v_mov_b32_e32 v197, v196
	v_permlane32_swap_b32_e32 v190, v191
	v_permlane32_swap_b32_e32 v192, v193
	v_permlane32_swap_b32_e32 v194, v195
	v_permlane32_swap_b32_e32 v196, v197
	v_add_f32_e32 v190, v190, v191
	v_add_f32_e32 v192, v192, v193
	v_add_f32_e32 v194, v194, v195
	v_add_f32_e32 v196, v196, v197
	v_mov_b32_e32 v191, v190
	v_mov_b32_e32 v193, v192
	v_mov_b32_e32 v195, v194
	v_mov_b32_e32 v197, v196
	v_permlane16_swap_b32_e32 v190, v191
	v_permlane16_swap_b32_e32 v192, v193
	v_permlane16_swap_b32_e32 v194, v195
	v_permlane16_swap_b32_e32 v196, v197
	v_add_f32_e32 v190, v190, v191
	v_add_f32_e32 v192, v192, v193
	v_add_f32_e32 v194, v194, v195
	v_add_f32_e32 v196, v196, v197
	v_add_f32_dpp v190, v190, v190 row_ror:8 row_mask:0xf bank_mask:0xf
	v_add_f32_dpp v192, v192, v192 row_ror:8 row_mask:0xf bank_mask:0xf
	v_add_f32_dpp v194, v194, v194 row_ror:8 row_mask:0xf bank_mask:0xf
	v_add_f32_dpp v196, v196, v196 row_ror:8 row_mask:0xf bank_mask:0xf
	v_add_f32_dpp v190, v190, v190 row_ror:4 row_mask:0xf bank_mask:0xf
	v_add_f32_dpp v192, v192, v192 row_ror:4 row_mask:0xf bank_mask:0xf
	v_add_f32_dpp v194, v194, v194 row_ror:4 row_mask:0xf bank_mask:0xf
	v_add_f32_dpp v196, v196, v196 row_ror:4 row_mask:0xf bank_mask:0xf
	v_add_f32_dpp v190, v190, v190 row_ror:2 row_mask:0xf bank_mask:0xf
	v_add_f32_dpp v192, v192, v192 row_ror:2 row_mask:0xf bank_mask:0xf
	v_add_f32_dpp v194, v194, v194 row_ror:2 row_mask:0xf bank_mask:0xf
	v_add_f32_dpp v196, v196, v196 row_ror:2 row_mask:0xf bank_mask:0xf
	v_add_f32_dpp v190, v190, v190 row_ror:1 row_mask:0xf bank_mask:0xf
	v_add_f32_dpp v192, v192, v192 row_ror:1 row_mask:0xf bank_mask:0xf
	v_add_f32_dpp v194, v194, v194 row_ror:1 row_mask:0xf bank_mask:0xf
	v_add_f32_dpp v196, v196, v196 row_ror:1 row_mask:0xf bank_mask:0xf
	v_fma_f32 v190, v190, v207, v206
	v_fma_f32 v192, v192, v207, v206
	v_fma_f32 v194, v194, v207, v206
	v_fma_f32 v196, v196, v207, v206
	v_mul_f32_e32 v210, 0x4b800000, v190
	v_cmp_gt_f32_e32 vcc, 0x800000, v190
	s_nop 1
	v_cndmask_b32_e32 v210, v190, v210, vcc
	v_rsq_f32_e32 v210, v210
	s_nop 0
	v_mul_f32_e32 v211, 0x45800000, v210
	v_cndmask_b32_e32 v190, v210, v211, vcc
	v_mul_f32_e32 v210, 0x4b800000, v192
	v_cmp_gt_f32_e32 vcc, 0x800000, v192
	s_nop 1
	v_cndmask_b32_e32 v210, v192, v210, vcc
	v_rsq_f32_e32 v210, v210
	s_nop 0
	v_mul_f32_e32 v211, 0x45800000, v210
	v_cndmask_b32_e32 v192, v210, v211, vcc
	v_mul_f32_e32 v210, 0x4b800000, v194
	v_cmp_gt_f32_e32 vcc, 0x800000, v194
	s_nop 1
	v_cndmask_b32_e32 v210, v194, v210, vcc
	v_rsq_f32_e32 v210, v210
	s_nop 0
	v_mul_f32_e32 v211, 0x45800000, v210
	v_cndmask_b32_e32 v194, v210, v211, vcc
	v_mul_f32_e32 v210, 0x4b800000, v196
	v_cmp_gt_f32_e32 vcc, 0x800000, v196
	s_nop 1
	v_cndmask_b32_e32 v210, v196, v210, vcc
	v_rsq_f32_e32 v210, v210
	s_nop 0
	v_mul_f32_e32 v211, 0x45800000, v210
	v_cndmask_b32_e32 v196, v210, v211, vcc
	s_waitcnt vmcnt(0)
	s_cmp_lg_u32 s64, 0
	s_cbranch_scc1 .Lln2_out_nomod
	v_pk_add_f32 v[118:119], v[118:119], 1.0 op_sel_hi:[1,0]
	v_pk_add_f32 v[120:121], v[120:121], 1.0 op_sel_hi:[1,0]
	v_pk_add_f32 v[122:123], v[122:123], 1.0 op_sel_hi:[1,0]
	v_pk_add_f32 v[124:125], v[124:125], 1.0 op_sel_hi:[1,0]
	v_pk_add_f32 v[126:127], v[126:127], 1.0 op_sel_hi:[1,0]
	v_pk_add_f32 v[128:129], v[128:129], 1.0 op_sel_hi:[1,0]
	v_pk_add_f32 v[130:131], v[130:131], 1.0 op_sel_hi:[1,0]
	v_pk_add_f32 v[132:133], v[132:133], 1.0 op_sel_hi:[1,0]
	v_pk_mul_f32 v[174:175], v[4:5], v[190:191] op_sel_hi:[1,0]
	v_pk_mul_f32 v[176:177], v[6:7], v[190:191] op_sel_hi:[1,0]
	v_pk_mul_f32 v[178:179], v[8:9], v[190:191] op_sel_hi:[1,0]
	v_pk_mul_f32 v[180:181], v[10:11], v[190:191] op_sel_hi:[1,0]
	v_pk_fma_f32 v[150:151], v[68:69], v[174:175], v[84:85]
	v_pk_fma_f32 v[152:153], v[70:71], v[176:177], v[86:87]
	v_pk_fma_f32 v[154:155], v[72:73], v[178:179], v[88:89]
	v_pk_fma_f32 v[156:157], v[74:75], v[180:181], v[90:91]
	global_store_dwordx4 v202, v[150:153], s[6:7]
	global_store_dwordx4 v202, v[154:157], s[6:7] offset:16
	v_pk_fma_f32 v[174:175], v[150:151], v[118:119], v[134:135]
	v_pk_fma_f32 v[176:177], v[152:153], v[120:121], v[136:137]
	v_pk_fma_f32 v[178:179], v[154:155], v[122:123], v[138:139]
	v_pk_fma_f32 v[180:181], v[156:157], v[124:125], v[140:141]
	v_cvt_pk_bf16_f32 v166, v174, v175
	v_cvt_pk_bf16_f32 v167, v176, v177
	v_cvt_pk_bf16_f32 v168, v178, v179
	v_cvt_pk_bf16_f32 v169, v180, v181
	global_store_dwordx4 v2, v[166:169], s[18:19]
	v_pk_mul_f32 v[174:175], v[12:13], v[190:191] op_sel_hi:[1,0]
	v_pk_mul_f32 v[176:177], v[14:15], v[190:191] op_sel_hi:[1,0]
	v_pk_mul_f32 v[178:179], v[16:17], v[190:191] op_sel_hi:[1,0]
	v_pk_mul_f32 v[180:181], v[18:19], v[190:191] op_sel_hi:[1,0]
	v_pk_fma_f32 v[158:159], v[76:77], v[174:175], v[92:93]
	v_pk_fma_f32 v[160:161], v[78:79], v[176:177], v[94:95]
	v_pk_fma_f32 v[162:163], v[80:81], v[178:179], v[96:97]
	v_pk_fma_f32 v[164:165], v[82:83], v[180:181], v[98:99]
	global_store_dwordx4 v202, v[158:161], s[6:7] offset:2048
	global_store_dwordx4 v202, v[162:165], s[6:7] offset:2064
	v_pk_fma_f32 v[174:175], v[158:159], v[126:127], v[142:143]
	v_pk_fma_f32 v[176:177], v[160:161], v[128:129], v[144:145]
	v_pk_fma_f32 v[178:179], v[162:163], v[130:131], v[146:147]
	v_pk_fma_f32 v[180:181], v[164:165], v[132:133], v[148:149]
	v_cvt_pk_bf16_f32 v170, v174, v175
	v_cvt_pk_bf16_f32 v171, v176, v177
	v_cvt_pk_bf16_f32 v172, v178, v179
	v_cvt_pk_bf16_f32 v173, v180, v181
	global_store_dwordx4 v2, v[170:173], s[18:19] offset:1024
	v_pk_mul_f32 v[174:175], v[20:21], v[192:193] op_sel_hi:[1,0]
	v_pk_mul_f32 v[176:177], v[22:23], v[192:193] op_sel_hi:[1,0]
	v_pk_mul_f32 v[178:179], v[24:25], v[192:193] op_sel_hi:[1,0]
	v_pk_mul_f32 v[180:181], v[26:27], v[192:193] op_sel_hi:[1,0]
	v_pk_fma_f32 v[150:151], v[68:69], v[174:175], v[84:85]
	v_pk_fma_f32 v[152:153], v[70:71], v[176:177], v[86:87]
	v_pk_fma_f32 v[154:155], v[72:73], v[178:179], v[88:89]
	v_pk_fma_f32 v[156:157], v[74:75], v[180:181], v[90:91]
	global_store_dwordx4 v203, v[150:153], s[6:7]
	global_store_dwordx4 v203, v[154:157], s[6:7] offset:16
	v_pk_fma_f32 v[174:175], v[150:151], v[118:119], v[134:135]
	v_pk_fma_f32 v[176:177], v[152:153], v[120:121], v[136:137]
	v_pk_fma_f32 v[178:179], v[154:155], v[122:123], v[138:139]
	v_pk_fma_f32 v[180:181], v[156:157], v[124:125], v[140:141]
	v_cvt_pk_bf16_f32 v166, v174, v175
	v_cvt_pk_bf16_f32 v167, v176, v177
	v_cvt_pk_bf16_f32 v168, v178, v179
	v_cvt_pk_bf16_f32 v169, v180, v181
	global_store_dwordx4 v2, v[166:169], s[18:19] offset:2048
	v_pk_mul_f32 v[174:175], v[28:29], v[192:193] op_sel_hi:[1,0]
	v_pk_mul_f32 v[176:177], v[30:31], v[192:193] op_sel_hi:[1,0]
	v_pk_mul_f32 v[178:179], v[32:33], v[192:193] op_sel_hi:[1,0]
	v_pk_mul_f32 v[180:181], v[34:35], v[192:193] op_sel_hi:[1,0]
	v_pk_fma_f32 v[158:159], v[76:77], v[174:175], v[92:93]
	v_pk_fma_f32 v[160:161], v[78:79], v[176:177], v[94:95]
	v_pk_fma_f32 v[162:163], v[80:81], v[178:179], v[96:97]
	v_pk_fma_f32 v[164:165], v[82:83], v[180:181], v[98:99]
	global_store_dwordx4 v203, v[158:161], s[6:7] offset:2048
	global_store_dwordx4 v203, v[162:165], s[6:7] offset:2064
	v_pk_fma_f32 v[174:175], v[158:159], v[126:127], v[142:143]
	v_pk_fma_f32 v[176:177], v[160:161], v[128:129], v[144:145]
	v_pk_fma_f32 v[178:179], v[162:163], v[130:131], v[146:147]
	v_pk_fma_f32 v[180:181], v[164:165], v[132:133], v[148:149]
	v_cvt_pk_bf16_f32 v170, v174, v175
	v_cvt_pk_bf16_f32 v171, v176, v177
	v_cvt_pk_bf16_f32 v172, v178, v179
	v_cvt_pk_bf16_f32 v173, v180, v181
	global_store_dwordx4 v2, v[170:173], s[18:19] offset:3072
	v_pk_mul_f32 v[174:175], v[36:37], v[194:195] op_sel_hi:[1,0]
	v_pk_mul_f32 v[176:177], v[38:39], v[194:195] op_sel_hi:[1,0]
	v_pk_mul_f32 v[178:179], v[40:41], v[194:195] op_sel_hi:[1,0]
	v_pk_mul_f32 v[180:181], v[42:43], v[194:195] op_sel_hi:[1,0]
	v_pk_fma_f32 v[150:151], v[68:69], v[174:175], v[84:85]
	v_pk_fma_f32 v[152:153], v[70:71], v[176:177], v[86:87]
	v_pk_fma_f32 v[154:155], v[72:73], v[178:179], v[88:89]
	v_pk_fma_f32 v[156:157], v[74:75], v[180:181], v[90:91]
	global_store_dwordx4 v204, v[150:153], s[6:7]
	global_store_dwordx4 v204, v[154:157], s[6:7] offset:16
	v_pk_fma_f32 v[174:175], v[150:151], v[118:119], v[134:135]
	v_pk_fma_f32 v[176:177], v[152:153], v[120:121], v[136:137]
	v_pk_fma_f32 v[178:179], v[154:155], v[122:123], v[138:139]
	v_pk_fma_f32 v[180:181], v[156:157], v[124:125], v[140:141]
	v_cvt_pk_bf16_f32 v166, v174, v175
	v_cvt_pk_bf16_f32 v167, v176, v177
	v_cvt_pk_bf16_f32 v168, v178, v179
	v_cvt_pk_bf16_f32 v169, v180, v181
	global_store_dwordx4 v3, v[166:169], s[18:19]
	v_pk_mul_f32 v[174:175], v[44:45], v[194:195] op_sel_hi:[1,0]
	v_pk_mul_f32 v[176:177], v[46:47], v[194:195] op_sel_hi:[1,0]
	v_pk_mul_f32 v[178:179], v[48:49], v[194:195] op_sel_hi:[1,0]
	v_pk_mul_f32 v[180:181], v[50:51], v[194:195] op_sel_hi:[1,0]
	v_pk_fma_f32 v[158:159], v[76:77], v[174:175], v[92:93]
	v_pk_fma_f32 v[160:161], v[78:79], v[176:177], v[94:95]
	v_pk_fma_f32 v[162:163], v[80:81], v[178:179], v[96:97]
	v_pk_fma_f32 v[164:165], v[82:83], v[180:181], v[98:99]
	global_store_dwordx4 v204, v[158:161], s[6:7] offset:2048
	global_store_dwordx4 v204, v[162:165], s[6:7] offset:2064
	v_pk_fma_f32 v[174:175], v[158:159], v[126:127], v[142:143]
	v_pk_fma_f32 v[176:177], v[160:161], v[128:129], v[144:145]
	v_pk_fma_f32 v[178:179], v[162:163], v[130:131], v[146:147]
	v_pk_fma_f32 v[180:181], v[164:165], v[132:133], v[148:149]
	v_cvt_pk_bf16_f32 v170, v174, v175
	v_cvt_pk_bf16_f32 v171, v176, v177
	v_cvt_pk_bf16_f32 v172, v178, v179
	v_cvt_pk_bf16_f32 v173, v180, v181
	global_store_dwordx4 v3, v[170:173], s[18:19] offset:1024
	v_pk_mul_f32 v[174:175], v[52:53], v[196:197] op_sel_hi:[1,0]
	v_pk_mul_f32 v[176:177], v[54:55], v[196:197] op_sel_hi:[1,0]
	v_pk_mul_f32 v[178:179], v[56:57], v[196:197] op_sel_hi:[1,0]
	v_pk_mul_f32 v[180:181], v[58:59], v[196:197] op_sel_hi:[1,0]
	v_pk_fma_f32 v[150:151], v[68:69], v[174:175], v[84:85]
	v_pk_fma_f32 v[152:153], v[70:71], v[176:177], v[86:87]
	v_pk_fma_f32 v[154:155], v[72:73], v[178:179], v[88:89]
	v_pk_fma_f32 v[156:157], v[74:75], v[180:181], v[90:91]
	global_store_dwordx4 v205, v[150:153], s[6:7]
	global_store_dwordx4 v205, v[154:157], s[6:7] offset:16
	v_pk_fma_f32 v[174:175], v[150:151], v[118:119], v[134:135]
	v_pk_fma_f32 v[176:177], v[152:153], v[120:121], v[136:137]
	v_pk_fma_f32 v[178:179], v[154:155], v[122:123], v[138:139]
	v_pk_fma_f32 v[180:181], v[156:157], v[124:125], v[140:141]
	v_cvt_pk_bf16_f32 v166, v174, v175
	v_cvt_pk_bf16_f32 v167, v176, v177
	v_cvt_pk_bf16_f32 v168, v178, v179
	v_cvt_pk_bf16_f32 v169, v180, v181
	global_store_dwordx4 v3, v[166:169], s[18:19] offset:2048
	v_pk_mul_f32 v[174:175], v[60:61], v[196:197] op_sel_hi:[1,0]
	v_pk_mul_f32 v[176:177], v[62:63], v[196:197] op_sel_hi:[1,0]
	v_pk_mul_f32 v[178:179], v[64:65], v[196:197] op_sel_hi:[1,0]
	v_pk_mul_f32 v[180:181], v[66:67], v[196:197] op_sel_hi:[1,0]
	v_pk_fma_f32 v[158:159], v[76:77], v[174:175], v[92:93]
	v_pk_fma_f32 v[160:161], v[78:79], v[176:177], v[94:95]
	v_pk_fma_f32 v[162:163], v[80:81], v[178:179], v[96:97]
	v_pk_fma_f32 v[164:165], v[82:83], v[180:181], v[98:99]
	global_store_dwordx4 v205, v[158:161], s[6:7] offset:2048
	global_store_dwordx4 v205, v[162:165], s[6:7] offset:2064
	v_pk_fma_f32 v[174:175], v[158:159], v[126:127], v[142:143]
	v_pk_fma_f32 v[176:177], v[160:161], v[128:129], v[144:145]
	v_pk_fma_f32 v[178:179], v[162:163], v[130:131], v[146:147]
	v_pk_fma_f32 v[180:181], v[164:165], v[132:133], v[148:149]
	v_cvt_pk_bf16_f32 v170, v174, v175
	v_cvt_pk_bf16_f32 v171, v176, v177
	v_cvt_pk_bf16_f32 v172, v178, v179
	v_cvt_pk_bf16_f32 v173, v180, v181
	global_store_dwordx4 v3, v[170:173], s[18:19] offset:3072
	s_branch .Lln2_next
.Lln2_out_nomod:
	v_pk_mul_f32 v[174:175], v[4:5], v[190:191] op_sel_hi:[1,0]
	v_pk_mul_f32 v[176:177], v[6:7], v[190:191] op_sel_hi:[1,0]
	v_pk_mul_f32 v[178:179], v[8:9], v[190:191] op_sel_hi:[1,0]
	v_pk_mul_f32 v[180:181], v[10:11], v[190:191] op_sel_hi:[1,0]
	v_pk_fma_f32 v[150:151], v[68:69], v[174:175], v[84:85]
	v_pk_fma_f32 v[152:153], v[70:71], v[176:177], v[86:87]
	v_pk_fma_f32 v[154:155], v[72:73], v[178:179], v[88:89]
	v_pk_fma_f32 v[156:157], v[74:75], v[180:181], v[90:91]
	global_store_dwordx4 v202, v[150:153], s[6:7]
	global_store_dwordx4 v202, v[154:157], s[6:7] offset:16
	v_pk_mul_f32 v[174:175], v[12:13], v[190:191] op_sel_hi:[1,0]
	v_pk_mul_f32 v[176:177], v[14:15], v[190:191] op_sel_hi:[1,0]
	v_pk_mul_f32 v[178:179], v[16:17], v[190:191] op_sel_hi:[1,0]
	v_pk_mul_f32 v[180:181], v[18:19], v[190:191] op_sel_hi:[1,0]
	v_pk_fma_f32 v[158:159], v[76:77], v[174:175], v[92:93]
	v_pk_fma_f32 v[160:161], v[78:79], v[176:177], v[94:95]
	v_pk_fma_f32 v[162:163], v[80:81], v[178:179], v[96:97]
	v_pk_fma_f32 v[164:165], v[82:83], v[180:181], v[98:99]
	global_store_dwordx4 v202, v[158:161], s[6:7] offset:2048
	global_store_dwordx4 v202, v[162:165], s[6:7] offset:2064
	v_pk_mul_f32 v[174:175], v[20:21], v[192:193] op_sel_hi:[1,0]
	v_pk_mul_f32 v[176:177], v[22:23], v[192:193] op_sel_hi:[1,0]
	v_pk_mul_f32 v[178:179], v[24:25], v[192:193] op_sel_hi:[1,0]
	v_pk_mul_f32 v[180:181], v[26:27], v[192:193] op_sel_hi:[1,0]
	v_pk_fma_f32 v[150:151], v[68:69], v[174:175], v[84:85]
	v_pk_fma_f32 v[152:153], v[70:71], v[176:177], v[86:87]
	v_pk_fma_f32 v[154:155], v[72:73], v[178:179], v[88:89]
	v_pk_fma_f32 v[156:157], v[74:75], v[180:181], v[90:91]
	global_store_dwordx4 v203, v[150:153], s[6:7]
	global_store_dwordx4 v203, v[154:157], s[6:7] offset:16
	v_pk_mul_f32 v[174:175], v[28:29], v[192:193] op_sel_hi:[1,0]
	v_pk_mul_f32 v[176:177], v[30:31], v[192:193] op_sel_hi:[1,0]
	v_pk_mul_f32 v[178:179], v[32:33], v[192:193] op_sel_hi:[1,0]
	v_pk_mul_f32 v[180:181], v[34:35], v[192:193] op_sel_hi:[1,0]
	v_pk_fma_f32 v[158:159], v[76:77], v[174:175], v[92:93]
	v_pk_fma_f32 v[160:161], v[78:79], v[176:177], v[94:95]
	v_pk_fma_f32 v[162:163], v[80:81], v[178:179], v[96:97]
	v_pk_fma_f32 v[164:165], v[82:83], v[180:181], v[98:99]
	global_store_dwordx4 v203, v[158:161], s[6:7] offset:2048
	global_store_dwordx4 v203, v[162:165], s[6:7] offset:2064
	v_pk_mul_f32 v[174:175], v[36:37], v[194:195] op_sel_hi:[1,0]
	v_pk_mul_f32 v[176:177], v[38:39], v[194:195] op_sel_hi:[1,0]
	v_pk_mul_f32 v[178:179], v[40:41], v[194:195] op_sel_hi:[1,0]
	v_pk_mul_f32 v[180:181], v[42:43], v[194:195] op_sel_hi:[1,0]
	v_pk_fma_f32 v[150:151], v[68:69], v[174:175], v[84:85]
	v_pk_fma_f32 v[152:153], v[70:71], v[176:177], v[86:87]
	v_pk_fma_f32 v[154:155], v[72:73], v[178:179], v[88:89]
	v_pk_fma_f32 v[156:157], v[74:75], v[180:181], v[90:91]
	global_store_dwordx4 v204, v[150:153], s[6:7]
	global_store_dwordx4 v204, v[154:157], s[6:7] offset:16
	v_pk_mul_f32 v[174:175], v[44:45], v[194:195] op_sel_hi:[1,0]
	v_pk_mul_f32 v[176:177], v[46:47], v[194:195] op_sel_hi:[1,0]
	v_pk_mul_f32 v[178:179], v[48:49], v[194:195] op_sel_hi:[1,0]
	v_pk_mul_f32 v[180:181], v[50:51], v[194:195] op_sel_hi:[1,0]
	v_pk_fma_f32 v[158:159], v[76:77], v[174:175], v[92:93]
	v_pk_fma_f32 v[160:161], v[78:79], v[176:177], v[94:95]
	v_pk_fma_f32 v[162:163], v[80:81], v[178:179], v[96:97]
	v_pk_fma_f32 v[164:165], v[82:83], v[180:181], v[98:99]
	global_store_dwordx4 v204, v[158:161], s[6:7] offset:2048
	global_store_dwordx4 v204, v[162:165], s[6:7] offset:2064
	v_pk_mul_f32 v[174:175], v[52:53], v[196:197] op_sel_hi:[1,0]
	v_pk_mul_f32 v[176:177], v[54:55], v[196:197] op_sel_hi:[1,0]
	v_pk_mul_f32 v[178:179], v[56:57], v[196:197] op_sel_hi:[1,0]
	v_pk_mul_f32 v[180:181], v[58:59], v[196:197] op_sel_hi:[1,0]
	v_pk_fma_f32 v[150:151], v[68:69], v[174:175], v[84:85]
	v_pk_fma_f32 v[152:153], v[70:71], v[176:177], v[86:87]
	v_pk_fma_f32 v[154:155], v[72:73], v[178:179], v[88:89]
	v_pk_fma_f32 v[156:157], v[74:75], v[180:181], v[90:91]
	global_store_dwordx4 v205, v[150:153], s[6:7]
	global_store_dwordx4 v205, v[154:157], s[6:7] offset:16
	v_pk_mul_f32 v[174:175], v[60:61], v[196:197] op_sel_hi:[1,0]
	v_pk_mul_f32 v[176:177], v[62:63], v[196:197] op_sel_hi:[1,0]
	v_pk_mul_f32 v[178:179], v[64:65], v[196:197] op_sel_hi:[1,0]
	v_pk_mul_f32 v[180:181], v[66:67], v[196:197] op_sel_hi:[1,0]
	v_pk_fma_f32 v[158:159], v[76:77], v[174:175], v[92:93]
	v_pk_fma_f32 v[160:161], v[78:79], v[176:177], v[94:95]
	v_pk_fma_f32 v[162:163], v[80:81], v[178:179], v[96:97]
	v_pk_fma_f32 v[164:165], v[82:83], v[180:181], v[98:99]
	global_store_dwordx4 v205, v[158:161], s[6:7] offset:2048
	global_store_dwordx4 v205, v[162:165], s[6:7] offset:2064
.Lln2_next:
	s_add_i32 s0, s0, 32
	s_branch .Lln2_loop
.Lln2_end:
	s_mov_b32 s64, 0
	s_mov_b64 s[8:9], exec
